# diff attention loop restructured: waves 0-3 MFMA-then-softmax, waves 4-7 softmax-then-MFMA, K one tile ahead of V
# speedup vs baseline: 1.0233x; 1.0233x over previous
; template <bool DIFF>
; __device__ __forceinline__ void attn_unit(const AttnP& A, int b, int h, int qi, ldsp lds) {
;     ...
;     const bf16* Pq = A.P + (Rb + q_pp) * NP;
;     bf16x8 qf[4];
; #pragma unroll
;     for (int c = 0; c < 4; ++c) qf[c] = *(const bf16x8*)(Pq + qcol + 16 * c + 8 * hi);
;     LAS float* pref = (LAS float*)(lds + LDS_PREF);
;     u32x4 kreg[NPIECE], vreg[NPIECE]; float clreg = 0.f;
;     ...
;     int kt0 = 0;
;     if (!DIFF) {
;         LAS int* kst = (LAS int*)(lds + LDS_MISC + 64);
;         if (tid == 0) *kst = nt - 1;
;         if (w == 0) {
;             float carry = 0.f;
; #pragma unroll
;             for (int ch = 0; ch < 3; ++ch) {
;                 const int idx = ch * 64 + lane;
;                 const float v = idx < TPB ? A.cumtot[(b * TPB + idx) * 8 + h] : 0.f;
;                 float inc = v;
; #pragma unroll
;                 for (int o = 1; o < 64; o <<= 1) { const float t_ = __shfl_up(inc, o); if (lane >= o) inc += t_; }
;                 if (idx < TPB) pref[idx] = carry + inc - v;
;                 if (idx == TPB - 1) pref[TPB] = carry + inc;
;                 carry += __shfl(inc, 63);
;             }
;         }
;         __syncthreads();
;         const float q2 = __uint_as_float(A.nrm[(h) * 2]) + __uint_as_float(A.nrm[(h) * 2 + 1]), k2r = __uint_as_float(A.nrm[(8 + h) * 2]) + __uint_as_float(A.nrm[(8 + h) * 2 + 1]),
;                     k2m = (__uint_as_float(A.nrm[32 + h * 4]) + __uint_as_float(A.nrm[32 + h * 4 + 1])) + (__uint_as_float(A.nrm[32 + h * 4 + 2]) + __uint_as_float(A.nrm[32 + h * 4 + 3])), k2 = fmaxf(k2r, k2m);
;         const float thr = 2.0f * 1.03f * sqrtf(q2 * k2) + 40.0f;
;         if (tid < nt) { if (pref[qstart >> 6] - pref[tid + 1] >= -thr) atomicMin((int*)kst, tid); }
;         __syncthreads();
;         kt0 = *kst;
;     }
;     LOAD_TILE(kt0);
;     STORE_TILE(kt0 & 1);
;     __syncthreads();
;     float cq = 0.f;
;     if (!DIFF) cq = pref[q_pp >> 6] + A.cumloc[(Rb + q_pp) * 8 + h];
;     float mhat = 0.f, l_run = 0.f;
;     f32x16 negm;
; #pragma unroll
;     for (int r = 0; r < 16; ++r) negm[r] = 0.f;
;     f32x16 o[NTD];
; #pragma unroll
;     for (int t = 0; t < NTD; ++t)
; #pragma unroll
;         for (int r = 0; r < 16; ++r) o[t][r] = 0.f;
;     const int trb = (4 * hi + ((lane & 15) >> 2)) * VP + ((lane >> 4) & 1) * 32 + (lane & 3) * 8;
;     for (int kt = kt0; kt < nt; ++kt) {
.LBB0_495:
	s_and_b64 vcc, exec, s[0:1]
	s_cbranch_vccz .LBB0_439
	s_mul_hi_i32 s0, s31, 0x7e07e07f
	s_lshr_b32 s1, s0, 31
	s_ashr_i32 s51, s0, 5
	s_add_i32 s51, s51, s1
	v_mov_b32_e32 v225, v200
	s_mul_i32 s0, s51, 0x41
	s_sub_i32 s0, s31, s0
	v_readfirstlane_b32 s64, v225
	s_ashr_i32 s22, s51, 2
	s_ashr_i32 s70, s64, 8
	s_bfe_u32 s65, s64, 0x20006
	s_cmp_eq_u32 s0, 0
	s_cselect_b64 s[24:25], -1, 0
	s_lshl_b32 s1, s0, 7
	s_sub_i32 s1, s1, 64
	s_cmp_lg_u32 s0, 0
	s_cselect_b64 s[16:17], -1, 0
	s_and_b64 s[40:41], s[16:17], exec
	s_cselect_b32 s1, s1, 0
	s_lshl_b32 s23, s65, 5
	v_and_b32_e32 v6, 31, v225
	s_add_i32 s1, s23, s1
	v_or_b32_e32 v192, s1, v6
	s_lshl_b32 s23, s51, 7
	v_ashrrev_i32_e32 v193, 31, v192
	s_and_b32 s50, s23, 0x180
	s_lshl_b32 s23, s70, 6
	v_mad_i64_i32 v[2:3], s[44:45], s22, v221, v[192:193]
	s_add_i32 s40, s23, s50
	v_lshlrev_b64 v[2:3], 13, v[2:3]
	v_bfe_u32 v7, v225, 5, 1
	v_lshl_add_u64 v[190:191], s[58:59], 0, v[2:3]
	s_ashr_i32 s41, s40, 31
	v_lshl_add_u64 v[2:3], s[40:41], 1, v[190:191]
	v_lshlrev_b32_e32 v194, 4, v7
	v_mov_b32_e32 v195, v1
	s_mul_i32 s41, s22, 0x4080000
	v_ashrrev_i32_e32 v8, 4, v225
	v_lshl_add_u64 v[2:3], v[2:3], 0, v[194:195]
	s_mul_hi_i32 s40, s22, 0x4080000
	s_add_u32 s44, s58, s41
	v_ashrrev_i32_e32 v9, 31, v8
	global_load_dwordx4 v[116:119], v[2:3], off
	global_load_dwordx4 v[120:123], v[2:3], off offset:32
	global_load_dwordx4 v[124:127], v[2:3], off offset:64
	global_load_dwordx4 v[128:131], v[2:3], off offset:96
	s_addc_u32 s45, s59, s40
	v_lshlrev_b64 v[2:3], 13, v[8:9]
	v_lshl_add_u64 v[4:5], s[44:45], 0, v[2:3]
	s_lshl_b32 s34, s50, 1
	v_lshlrev_b32_e32 v0, 4, v225
	v_lshl_add_u64 v[4:5], v[4:5], 0, s[34:35]
	v_and_b32_e32 v0, 0xf0, v0
	v_lshl_add_u64 v[4:5], v[4:5], 0, v[0:1]
	global_load_dwordx4 v[132:135], v[4:5], off offset:1024
	global_load_dwordx4 v[136:139], v[4:5], off offset:2048
	v_add_u32_e32 v4, 0x200, v225
	v_ashrrev_i32_e32 v10, 4, v4
	v_ashrrev_i32_e32 v11, 31, v10
	v_lshlrev_b64 v[4:5], 13, v[10:11]
	v_lshl_add_u64 v[12:13], s[44:45], 0, v[4:5]
	v_lshl_add_u64 v[12:13], v[12:13], 0, s[34:35]
	v_lshl_add_u64 v[12:13], v[12:13], 0, v[0:1]
	global_load_dwordx4 v[140:143], v[12:13], off offset:1024
	global_load_dwordx4 v[144:147], v[12:13], off offset:2048
	s_movk_i32 s23, 0x110
	v_add_u32_e32 v195, 0, v0
	v_mul_lo_u32 v226, v8, s23
	s_movk_i32 s44, 0x140
	v_add_u32_e32 v0, v195, v226
	v_mul_lo_u32 v227, v8, s44
	v_mul_lo_u32 v228, v10, s23
	v_mul_lo_u32 v229, v10, s44
	v_lshlrev_b32_e32 v115, 2, v7
	s_cmp_lt_i32 s0, 0
	s_waitcnt vmcnt(3)
	ds_write_b128 v0, v[132:135]
	v_add_u32_e32 v0, v195, v227
	s_waitcnt vmcnt(2)
	ds_write_b128 v0, v[136:139] offset:17408
	v_add_u32_e32 v0, v195, v228
	s_waitcnt vmcnt(1)
	ds_write_b128 v0, v[140:143]
	v_add_u32_e32 v0, v195, v229
	s_waitcnt vmcnt(0)
	ds_write_b128 v0, v[144:147] offset:17408
	s_waitcnt lgkmcnt(0)
	s_barrier
	s_cbranch_scc1 .LBB0_514
	s_lshl_b32 s23, s0, 1
	s_or_b32 s71, s1, 31
	s_lshl_b32 s0, s31, 1
	s_mul_i32 s1, s51, 0x82
	s_sub_i32 s0, s0, s1
	s_or_b32 s31, s0, 1
	s_and_b32 s0, s51, 3
	s_add_i32 s72, s23, -1
	s_lshl_b32 s73, s70, 7
	s_lshl_b32 s0, s0, 8
	s_add_u32 s0, s36, s0
	v_lshrrev_b32_e32 v7, 2, v225
	s_addc_u32 s1, s37, 0
	v_and_or_b32 v7, v7, 3, v115
	s_add_u32 s0, s0, s41
	v_lshlrev_b32_e32 v0, 3, v225
	v_mul_u32_u24_e32 v231, 0x140, v7
	v_lshlrev_b32_e32 v7, 1, v225
	s_addc_u32 s1, s1, s40
	v_mov_b32_e32 v16, v1
	v_mov_b32_e32 v17, v1
	v_and_b32_e32 v232, 32, v7
	v_and_b32_e32 v233, 24, v0
	v_mul_u32_u24_e32 v234, 0x110, v6
	v_and_b32_e32 v0, 15, v225
	v_lshl_add_u64 v[196:197], s[0:1], 0, v[2:3]
	v_lshl_add_u64 v[198:199], s[0:1], 0, v[4:5]
	v_mov_b32_e32 v2, v1
	v_mov_b32_e32 v3, v1
	v_mov_b32_e32 v4, v1
	v_mov_b32_e32 v5, v1
	v_mov_b32_e32 v6, v1
	v_mov_b32_e32 v7, v1
	v_mov_b32_e32 v8, v1
	v_mov_b32_e32 v9, v1
	v_mov_b32_e32 v10, v1
	v_mov_b32_e32 v11, v1
	v_mov_b32_e32 v12, v1
	v_mov_b32_e32 v13, v1
	v_mov_b32_e32 v14, v1
	v_mov_b32_e32 v15, v1
	v_mov_b32_e32 v235, 0
	v_mov_b64_e32 v[32:33], v[16:17]
	v_mov_b64_e32 v[48:49], v[16:17]
	v_mov_b64_e32 v[64:65], v[16:17]
	v_lshlrev_b32_e32 v0, 4, v0
	s_mov_b32 s74, 0
	v_mov_b64_e32 v[30:31], v[14:15]
	v_mov_b64_e32 v[28:29], v[12:13]
	v_mov_b64_e32 v[26:27], v[10:11]
	v_mov_b64_e32 v[24:25], v[8:9]
	v_mov_b64_e32 v[22:23], v[6:7]
	v_mov_b64_e32 v[20:21], v[4:5]
	v_mov_b64_e32 v[18:19], v[2:3]
	v_mov_b64_e32 v[46:47], v[14:15]
	v_mov_b64_e32 v[44:45], v[12:13]
	v_mov_b64_e32 v[42:43], v[10:11]
	v_mov_b64_e32 v[40:41], v[8:9]
	v_mov_b64_e32 v[38:39], v[6:7]
	v_mov_b64_e32 v[36:37], v[4:5]
	v_mov_b64_e32 v[34:35], v[2:3]
	v_mov_b64_e32 v[62:63], v[14:15]
	v_mov_b64_e32 v[60:61], v[12:13]
	v_mov_b64_e32 v[58:59], v[10:11]
	v_mov_b64_e32 v[56:57], v[8:9]
	v_mov_b64_e32 v[54:55], v[6:7]
	v_mov_b64_e32 v[52:53], v[4:5]
	v_mov_b64_e32 v[50:51], v[2:3]
	v_mov_b32_e32 v230, 0
	s_mov_b32 s75, 0
	v_mov_b32_e32 v66, 0
	v_mov_b32_e32 v67, v235
	v_mov_b32_e32 v68, v235
	v_mov_b32_e32 v69, v235
	v_mov_b32_e32 v70, v235
	v_mov_b32_e32 v71, v235
	v_mov_b32_e32 v72, v235
	v_mov_b32_e32 v73, v235
	v_mov_b32_e32 v74, v235
	v_mov_b32_e32 v75, v235
	v_mov_b32_e32 v76, v235
	v_mov_b32_e32 v77, v235
	v_mov_b32_e32 v78, v235
	v_mov_b32_e32 v79, v235
	v_mov_b32_e32 v80, v235
	v_mov_b32_e32 v81, v235
	s_lshr_b32 s44, s71, 6
	s_add_i32 s44, s44, 1
	s_min_i32 s44, s44, s31
	v_add_u32_e32 v226, v195, v226
	v_add_u32_e32 v227, v195, v227
	v_add_u32_e32 v228, v195, v228
	v_add_u32_e32 v229, v195, v229
	v_add3_u32 v231, v231, v232, v233
	v_add3_u32 v234, v234, v194, s73
	v_lshl_add_u64 v[196:197], v[196:197], 0, v[0:1]
	v_lshl_add_u64 v[198:199], v[198:199], 0, v[0:1]
	v_add_co_u32_e32 v196, vcc, 0x5c00000, v196
	s_nop 1
	v_addc_co_u32_e32 v197, vcc, 0, v197, vcc
	v_add_co_u32_e32 v198, vcc, 0x5c00000, v198
	s_nop 1
	v_addc_co_u32_e32 v199, vcc, 0, v199, vcc
	s_cmp_lg_u32 s70, 0
	s_cbranch_scc1 .Ldb_top
; __device__ __forceinline__ s16x4 vtr(ldsp p) { return __builtin_bit_cast(s16x4, __builtin_amdgcn_ds_read_tr16_b64_v4i16((LAS v4i16_t*)p)); }
; template <bool DIFF>
; __device__ __forceinline__ void attn_unit(const AttnP& A, int b, int h, int qi, ldsp lds) {
;     ...
;     for (int kt = kt0; kt < nt; ++kt) {
;         if (kt + 1 < nt) LOAD_TILE(kt + 1);
;         if (64 * kt <= qmax_w) {
;             ldsp Kb = lds + (kt & 1) * STAGE; ldsp Vb = Kb + 64 * KP;
;             bf16x8 kf[8]; bf16x8 ka0, ka1, qa; f32x16 s0, s1;
;     ...
;             QK_BLOCK();
;             s16x4 vlo[8], vhi[8];
; #pragma unroll
;             for (int t = 0; t < 2; ++t)
; #pragma unroll
;                 for (int j = 0; j < 4; ++j) { vlo[t * 4 + j] = vtr(Vb + trb + (16 * j) * VP + t * 64); vhi[t * 4 + j] = vtr(Vb + trb + (16 * j + 8) * VP + t * 64); }
;     ...
; #pragma unroll
;             for (int t = 0; t < 2; ++t)
; #pragma unroll
;                 for (int j = 0; j < 4; ++j) {
;                     const bf16x8 vf = (bf16x8){vlo[t * 4 + j][0], vlo[t * 4 + j][1], vlo[t * 4 + j][2], vlo[t * 4 + j][3], vhi[t * 4 + j][0], vhi[t * 4 + j][1], vhi[t * 4 + j][2], vhi[t * 4 + j][3]};
;                     o[t] = __builtin_amdgcn_mfma_f32_32x32x16_bf16(vf, pw[j], o[t], 0, 0, 0);
;                 }
;             if (DIFF) {
; #pragma unroll
;                 for (int t = 2; t < NTD; ++t)
; #pragma unroll
;                     for (int j = 0; j < 4; ++j) { vlo[(t - 2) * 4 + j] = vtr(Vb + trb + (16 * j) * VP + t * 64); vhi[(t - 2) * 4 + j] = vtr(Vb + trb + (16 * j + 8) * VP + t * 64); }
;                 __builtin_amdgcn_sched_barrier(0);
; #pragma unroll
;                 for (int t = 2; t < NTD; ++t)
; #pragma unroll
;                     for (int j = 0; j < 4; ++j) {
;                         const int i = (t - 2) * 4 + j;
;                         const bf16x8 vf = (bf16x8){vlo[i][0], vlo[i][1], vlo[i][2], vlo[i][3], vhi[i][0], vhi[i][1], vhi[i][2], vhi[i][3]};
;                         o[t] = __builtin_amdgcn_mfma_f32_32x32x16_bf16(vf, pw[j], o[t], 0, 0, 0);
;                     }
;             }
;             __builtin_amdgcn_s_setprio(0);
;         }
;         if (kt + 1 < nt) STORE_TILE((kt + 1) & 1);
.Lda_top:
	s_bitcmp1_b32 s75, 0
	s_cselect_b32 s45, 0x9500, 0
	s_sub_i32 s71, 0x9500, s45
	s_cmp_ge_i32 s75, s31
	s_cbranch_scc1 .Lda1_nov
	s_cmp_eq_u32 s75, 0
	s_cbranch_scc1 .Lda1_nov
	global_load_dwordx4 v[136:139], v[196:197], off offset:2048
	global_load_dwordx4 v[144:147], v[198:199], off offset:2048
.Lda1_nov:
	v_lshl_add_u64 v[196:197], v[196:197], 0, s[26:27]
	v_lshl_add_u64 v[198:199], v[198:199], 0, s[26:27]
	s_add_i32 s0, s75, 1
	s_cmp_ge_i32 s0, s31
	s_cbranch_scc1 .Lda2_nok
	global_load_dwordx4 v[132:135], v[196:197], off offset:1024
	global_load_dwordx4 v[140:143], v[198:199], off offset:1024
.Lda2_nok:
	s_cmp_eq_u32 s75, 0
	s_cbranch_scc1 .Lda_first
	s_cmp_gt_i32 s75, s44
	s_cbranch_scc1 .Lda_idle
	s_cmp_eq_u32 s75, s44
	s_cbranch_scc1 .Lda_last
	v_add_u32_e32 v239, s45, v234
	v_add_u32_e32 v236, s71, v231
	ds_read_b64_tr_b16 v[148:149], v236 offset:17472
	ds_read_b64_tr_b16 v[150:151], v236 offset:20032
	ds_read_b64_tr_b16 v[152:153], v236 offset:17408
	ds_read_b64_tr_b16 v[154:155], v236 offset:19968
	ds_read_b64_tr_b16 v[156:157], v236 offset:22592
	ds_read_b64_tr_b16 v[158:159], v236 offset:25152
	ds_read_b64_tr_b16 v[160:161], v236 offset:22528
	ds_read_b64_tr_b16 v[162:163], v236 offset:25088
	ds_read_b64_tr_b16 v[164:165], v236 offset:27712
	ds_read_b64_tr_b16 v[166:167], v236 offset:30272
	ds_read_b64_tr_b16 v[168:169], v236 offset:27648
	ds_read_b64_tr_b16 v[170:171], v236 offset:30208
	ds_read_b64_tr_b16 v[172:173], v236 offset:32768
	ds_read_b64_tr_b16 v[174:175], v236 offset:35328
	ds_read_b64_tr_b16 v[176:177], v236 offset:32832
	ds_read_b64_tr_b16 v[178:179], v236 offset:35392
	s_waitcnt lgkmcnt(14)
	v_mfma_f32_32x32x16_bf16 v[34:49], v[148:151], v[98:101], v[34:49]
	ds_read_b64_tr_b16 v[90:91], v236 offset:17536
	ds_read_b64_tr_b16 v[92:93], v236 offset:20096
	s_waitcnt lgkmcnt(14)
	v_mfma_f32_32x32x16_bf16 v[50:65], v[152:155], v[98:101], v[50:65]
	ds_read_b64_tr_b16 v[94:95], v236 offset:17600
	ds_read_b64_tr_b16 v[96:97], v236 offset:20160
	s_waitcnt lgkmcnt(14)
	v_mfma_f32_32x32x16_bf16 v[34:49], v[156:159], v[102:105], v[34:49]
	ds_read_b64_tr_b16 v[106:107], v236 offset:22656
	ds_read_b64_tr_b16 v[108:109], v236 offset:25216
	s_waitcnt lgkmcnt(14)
	v_mfma_f32_32x32x16_bf16 v[50:65], v[160:163], v[102:105], v[50:65]
	ds_read_b64_tr_b16 v[110:111], v236 offset:22720
	ds_read_b64_tr_b16 v[112:113], v236 offset:25280
	s_waitcnt lgkmcnt(14)
	v_mfma_f32_32x32x16_bf16 v[34:49], v[164:167], v[82:85], v[34:49]
	ds_read_b64_tr_b16 v[240:241], v236 offset:27776
	ds_read_b64_tr_b16 v[242:243], v236 offset:30336
	s_waitcnt lgkmcnt(14)
	v_mfma_f32_32x32x16_bf16 v[50:65], v[168:171], v[82:85], v[50:65]
	ds_read_b64_tr_b16 v[148:149], v236 offset:27840
	ds_read_b64_tr_b16 v[150:151], v236 offset:30400
	s_waitcnt lgkmcnt(14)
	v_mfma_f32_32x32x16_bf16 v[50:65], v[172:175], v[86:89], v[50:65]
	ds_read_b64_tr_b16 v[152:153], v236 offset:32896
	ds_read_b64_tr_b16 v[154:155], v236 offset:35456
	s_waitcnt lgkmcnt(14)
	v_mfma_f32_32x32x16_bf16 v[34:49], v[176:179], v[86:89], v[34:49]
	ds_read_b64_tr_b16 v[156:157], v236 offset:32960
	ds_read_b64_tr_b16 v[158:159], v236 offset:35520
	s_waitcnt lgkmcnt(14)
	v_mfma_f32_32x32x16_bf16 v[18:33], v[90:93], v[98:101], v[18:33]
	ds_read_b128 v[160:163], v239
	s_waitcnt lgkmcnt(13)
	v_mfma_f32_32x32x16_bf16 v[2:17], v[94:97], v[98:101], v[2:17]
	ds_read_b128 v[164:167], v239 offset:8704
	s_waitcnt lgkmcnt(12)
	v_mfma_f32_32x32x16_bf16 v[18:33], v[106:109], v[102:105], v[18:33]
	ds_read_b128 v[168:171], v239 offset:32
	s_waitcnt lgkmcnt(11)
	v_mfma_f32_32x32x16_bf16 v[2:17], v[110:113], v[102:105], v[2:17]
	ds_read_b128 v[172:175], v239 offset:8736
	s_waitcnt lgkmcnt(10)
	v_mfma_f32_32x32x16_bf16 v[18:33], v[240:243], v[82:85], v[18:33]
	ds_read_b128 v[176:179], v239 offset:64
	s_waitcnt lgkmcnt(9)
	v_mfma_f32_32x32x16_bf16 v[2:17], v[148:151], v[82:85], v[2:17]
	ds_read_b128 v[240:243], v239 offset:8768
	s_waitcnt lgkmcnt(8)
	v_mfma_f32_32x32x16_bf16 v[18:33], v[152:155], v[86:89], v[18:33]
	ds_read_b128 v[148:151], v239 offset:96
	s_waitcnt lgkmcnt(7)
	v_mfma_f32_32x32x16_bf16 v[2:17], v[156:159], v[86:89], v[2:17]
	ds_read_b128 v[152:155], v239 offset:8800
	s_waitcnt lgkmcnt(7)
	v_mfma_f32_32x32x16_bf16 v[98:113], v[160:163], v[116:119], v[66:81]
	s_waitcnt lgkmcnt(6)
	v_mfma_f32_32x32x16_bf16 v[82:97], v[164:167], v[116:119], v[66:81]
	s_waitcnt lgkmcnt(5)
	v_mfma_f32_32x32x16_bf16 v[98:113], v[168:171], v[120:123], v[98:113]
	s_waitcnt lgkmcnt(4)
	v_mfma_f32_32x32x16_bf16 v[82:97], v[172:175], v[120:123], v[82:97]
	s_waitcnt lgkmcnt(3)
	v_mfma_f32_32x32x16_bf16 v[98:113], v[176:179], v[124:127], v[98:113]
	s_waitcnt lgkmcnt(2)
	v_mfma_f32_32x32x16_bf16 v[82:97], v[240:243], v[124:127], v[82:97]
	s_waitcnt lgkmcnt(1)
	v_mfma_f32_32x32x16_bf16 v[98:113], v[148:151], v[128:131], v[98:113]
	s_waitcnt lgkmcnt(0)
	v_mfma_f32_32x32x16_bf16 v[82:97], v[152:155], v[128:131], v[82:97]
.Lda_postqk:
	s_waitcnt vmcnt(0)
	s_add_i32 s0, s75, 1
	s_cmp_ge_i32 s0, s31
	s_cbranch_scc1 .Lda4_snok
	v_add_u32_e32 v204, s71, v226
	ds_write_b128 v204, v[132:135]
	v_add_u32_e32 v205, s71, v228
	ds_write_b128 v205, v[140:143]
.Lda4_snok:
	s_cmp_ge_i32 s75, s31
	s_cbranch_scc1 .Lda3_snov
	s_cmp_eq_u32 s75, 0
	s_cbranch_scc1 .Lda3_snov
	v_add_u32_e32 v204, s45, v227
	ds_write_b128 v204, v[136:139] offset:17408
	v_add_u32_e32 v205, s45, v229
	ds_write_b128 v205, v[144:147] offset:17408
; __device__ __forceinline__ s16x4 vtr(ldsp p) { return __builtin_bit_cast(s16x4, __builtin_amdgcn_ds_read_tr16_b64_v4i16((LAS v4i16_t*)p)); }
; #define MASK_BLOCK() do { if (kt == 0 || kt >= diag0) { \
;             _Pragma("unroll") for (int r = 0; r < 16; ++r) { const int kpp = 64 * kt + crow(r, hi); \
;                 if (kpp < 48 || kpp > q_pp) s0[r] = -INFINITY; \
;                 if (kpp + 32 < 48 || kpp + 32 > q_pp) s1[r] = -INFINITY; } } } while (0)
; #define EXPSUM_BLOCK() do { psa = 0.f; psb = 0.f; \
;             _Pragma("unroll") for (int r = 0; r < 16; ++r) { s0[r] = __builtin_amdgcn_exp2f(s0[r]); s1[r] = __builtin_amdgcn_exp2f(s1[r]); psa += s0[r]; asm("" : "+v"(psa)); psb += s1[r]; asm("" : "+v"(psb)); } } while (0)
; template <bool DIFF>
; __device__ __forceinline__ void attn_unit(const AttnP& A, int b, int h, int qi, ldsp lds) {
;     ...
;             QK_BLOCK();
;             s16x4 vlo[8], vhi[8];
; #pragma unroll
;             for (int t = 0; t < 2; ++t)
; #pragma unroll
;                 for (int j = 0; j < 4; ++j) { vlo[t * 4 + j] = vtr(Vb + trb + (16 * j) * VP + t * 64); vhi[t * 4 + j] = vtr(Vb + trb + (16 * j + 8) * VP + t * 64); }
;             __builtin_amdgcn_sched_barrier(0);
;             MASK_BLOCK();
;             bool full = (kt == kt0);
;             float psa, psb;
;             if (!full) {
;                 EXPSUM_BLOCK();
;                 if (__any(psa + psb > 1.0e18f)) { full = true; QK_BLOCK();
; #pragma unroll
;                     for (int t = 0; t < 2; ++t)
; #pragma unroll
;                         for (int j = 0; j < 4; ++j) { vlo[t * 4 + j] = vtr(Vb + trb + (16 * j) * VP + t * 64); vhi[t * 4 + j] = vtr(Vb + trb + (16 * j + 8) * VP + t * 64); }
;                     MASK_BLOCK(); }
;             }
.Lda3_snov:
	s_nop 7
	s_nop 3
	s_cmp_eq_u32 s74, 0
	s_cselect_b64 s[40:41], -1, 0
	s_cselect_b64 s[48:49], 0, -1
	s_lshr_b32 s0, s74, 6
	s_cmp_ge_i32 s0, s72
	s_cselect_b64 s[46:47], -1, 0
	s_or_b64 s[46:47], s[46:47], s[40:41]
	s_or_b64 s[46:47], s[46:47], s[24:25]
	s_and_b64 vcc, exec, s[46:47]
	s_cbranch_vccz .Lda5_nomask
	v_add_u32_e32 v204, s74, v115
	v_cmp_gt_i32_e32 vcc, v204, v192
	s_or_b64 vcc, s[40:41], vcc
	v_add_u32_e32 v205, 32, v204
	v_cndmask_b32_e32 v98, v98, v223, vcc
	v_cmp_gt_i32_e32 vcc, v205, v192
	s_or_b64 vcc, s[40:41], vcc
	v_add_u32_e32 v205, 33, v204
	v_cndmask_b32_e32 v82, v82, v223, vcc
	v_cmp_ge_i32_e32 vcc, v204, v192
	s_or_b64 vcc, s[40:41], vcc
	s_nop 0
	v_cndmask_b32_e32 v99, v99, v223, vcc
	v_cmp_gt_i32_e32 vcc, v205, v192
	s_or_b64 vcc, s[40:41], vcc
	v_add_u32_e32 v205, 2, v204
	v_cndmask_b32_e32 v83, v83, v223, vcc
	v_cmp_gt_i32_e32 vcc, v205, v192
	s_or_b64 vcc, s[40:41], vcc
	v_add_u32_e32 v205, 34, v204
	v_cndmask_b32_e32 v100, v100, v223, vcc
	v_cmp_gt_i32_e32 vcc, v205, v192
	s_or_b64 vcc, s[40:41], vcc
	v_add_u32_e32 v205, 3, v204
	v_cndmask_b32_e32 v84, v84, v223, vcc
	v_cmp_gt_i32_e32 vcc, v205, v192
	s_or_b64 vcc, s[40:41], vcc
	v_add_u32_e32 v205, 35, v204
	v_cndmask_b32_e32 v101, v101, v223, vcc
	v_cmp_gt_i32_e32 vcc, v205, v192
	s_or_b64 vcc, s[40:41], vcc
	v_add_u32_e32 v205, 8, v204
	v_cndmask_b32_e32 v85, v85, v223, vcc
	v_cmp_gt_i32_e32 vcc, v205, v192
	s_or_b64 vcc, s[40:41], vcc
	v_add_u32_e32 v205, 40, v204
	v_cndmask_b32_e32 v102, v102, v223, vcc
	v_cmp_gt_i32_e32 vcc, v205, v192
	s_or_b64 vcc, s[40:41], vcc
	v_add_u32_e32 v205, 9, v204
	v_cndmask_b32_e32 v86, v86, v223, vcc
	v_cmp_gt_i32_e32 vcc, v205, v192
	s_or_b64 vcc, s[40:41], vcc
	v_add_u32_e32 v205, 41, v204
	v_cndmask_b32_e32 v103, v103, v223, vcc
	v_cmp_gt_i32_e32 vcc, v205, v192
	s_or_b64 vcc, s[40:41], vcc
	v_add_u32_e32 v205, 10, v204
	v_cndmask_b32_e32 v87, v87, v223, vcc
	v_cmp_gt_i32_e32 vcc, v205, v192
	s_or_b64 vcc, s[40:41], vcc
	v_add_u32_e32 v205, 42, v204
	v_cndmask_b32_e32 v104, v104, v223, vcc
	v_cmp_gt_i32_e32 vcc, v205, v192
	s_or_b64 vcc, s[40:41], vcc
	v_add_u32_e32 v205, 11, v204
	v_cndmask_b32_e32 v88, v88, v223, vcc
	v_cmp_gt_i32_e32 vcc, v205, v192
	s_or_b64 vcc, s[40:41], vcc
	v_add_u32_e32 v205, 43, v204
	v_cndmask_b32_e32 v105, v105, v223, vcc
	v_cmp_gt_i32_e32 vcc, v205, v192
	s_or_b64 vcc, s[40:41], vcc
	v_add_u32_e32 v205, 16, v204
	v_cndmask_b32_e32 v89, v89, v223, vcc
	v_cmp_gt_u32_e32 vcc, 48, v205
	v_cmp_gt_i32_e64 s[46:47], v205, v192
	s_or_b64 vcc, vcc, s[46:47]
	v_add_u32_e32 v205, 48, v204
	v_cndmask_b32_e32 v106, v106, v223, vcc
	v_cmp_le_i32_e32 vcc, v205, v192
	v_add_u32_e32 v205, 17, v204
	v_cmp_gt_i32_e64 s[46:47], v205, v192
	v_cndmask_b32_e32 v90, v223, v90, vcc
	v_cmp_gt_u32_e32 vcc, 48, v205
	s_or_b64 vcc, vcc, s[46:47]
	v_add_u32_e32 v205, 49, v204
	v_cndmask_b32_e32 v107, v107, v223, vcc
	v_cmp_le_i32_e32 vcc, v205, v192
	v_add_u32_e32 v205, 18, v204
	v_cmp_gt_i32_e64 s[46:47], v205, v192
	v_cndmask_b32_e32 v91, v223, v91, vcc
	v_cmp_gt_u32_e32 vcc, 48, v205
	s_or_b64 vcc, vcc, s[46:47]
	v_add_u32_e32 v205, 50, v204
	v_cndmask_b32_e32 v108, v108, v223, vcc
	v_cmp_le_i32_e32 vcc, v205, v192
	v_add_u32_e32 v205, 19, v204
	v_cmp_gt_i32_e64 s[46:47], v205, v192
	v_cndmask_b32_e32 v92, v223, v92, vcc
	v_cmp_gt_u32_e32 vcc, 48, v205
	s_or_b64 vcc, vcc, s[46:47]
	v_add_u32_e32 v205, 51, v204
	v_cndmask_b32_e32 v109, v109, v223, vcc
	v_cmp_le_i32_e32 vcc, v205, v192
	v_add_u32_e32 v205, 24, v204
	v_cmp_gt_i32_e64 s[46:47], v205, v192
	v_cndmask_b32_e32 v93, v223, v93, vcc
	v_cmp_gt_u32_e32 vcc, 48, v205
	s_or_b64 vcc, vcc, s[46:47]
	v_add_u32_e32 v205, 56, v204
	v_cndmask_b32_e32 v110, v110, v223, vcc
	v_cmp_le_i32_e32 vcc, v205, v192
	v_add_u32_e32 v205, 25, v204
	v_cmp_gt_i32_e64 s[46:47], v205, v192
	v_cndmask_b32_e32 v94, v223, v94, vcc
	v_cmp_gt_u32_e32 vcc, 48, v205
	s_or_b64 vcc, vcc, s[46:47]
	v_add_u32_e32 v205, 57, v204
	v_cndmask_b32_e32 v111, v111, v223, vcc
	v_cmp_le_i32_e32 vcc, v205, v192
	v_add_u32_e32 v205, 26, v204
	v_cmp_gt_i32_e64 s[46:47], v205, v192
	v_cndmask_b32_e32 v95, v223, v95, vcc
	v_cmp_gt_u32_e32 vcc, 48, v205
	s_or_b64 vcc, vcc, s[46:47]
	v_add_u32_e32 v205, 58, v204
	v_cndmask_b32_e32 v112, v112, v223, vcc
	v_cmp_le_i32_e32 vcc, v205, v192
	v_add_u32_e32 v205, 27, v204
	v_cmp_gt_i32_e64 s[46:47], v205, v192
	v_cndmask_b32_e32 v96, v223, v96, vcc
	v_cmp_gt_u32_e32 vcc, 48, v205
	s_or_b64 vcc, vcc, s[46:47]
	v_add_u32_e32 v204, 59, v204
	v_cndmask_b32_e32 v113, v113, v223, vcc
	v_cmp_le_i32_e32 vcc, v204, v192
	s_nop 1
	v_cndmask_b32_e32 v97, v223, v97, vcc
.Lda5_nomask:
	s_and_b64 vcc, exec, s[40:41]
	s_cbranch_vccnz .Lda6_full
	v_exp_f32_e32 v148, v98
	v_exp_f32_e32 v164, v82
	v_exp_f32_e32 v149, v99
	v_exp_f32_e32 v165, v83
	v_add_f32_e32 v237, 0, v148
	v_add_f32_e32 v238, 0, v164
	v_exp_f32_e32 v150, v100
	v_exp_f32_e32 v166, v84
	v_add_f32_e32 v237, v149, v237
	v_add_f32_e32 v238, v165, v238
	v_exp_f32_e32 v151, v101
	v_exp_f32_e32 v167, v85
	v_add_f32_e32 v237, v150, v237
	v_add_f32_e32 v238, v166, v238
	v_exp_f32_e32 v152, v102
	v_exp_f32_e32 v168, v86
	v_add_f32_e32 v237, v151, v237
	v_add_f32_e32 v238, v167, v238
	v_exp_f32_e32 v153, v103
	v_exp_f32_e32 v169, v87
	v_add_f32_e32 v237, v152, v237
	v_add_f32_e32 v238, v168, v238
	v_exp_f32_e32 v154, v104
	v_exp_f32_e32 v170, v88
	v_add_f32_e32 v237, v153, v237
	v_add_f32_e32 v238, v169, v238
	v_exp_f32_e32 v155, v105
	v_exp_f32_e32 v171, v89
	v_add_f32_e32 v237, v154, v237
	v_add_f32_e32 v238, v170, v238
	v_exp_f32_e32 v156, v106
	v_exp_f32_e32 v172, v90
	v_add_f32_e32 v237, v155, v237
	v_add_f32_e32 v238, v171, v238
	v_exp_f32_e32 v157, v107
	v_exp_f32_e32 v173, v91
	v_add_f32_e32 v237, v156, v237
	v_add_f32_e32 v238, v172, v238
	v_exp_f32_e32 v158, v108
	v_exp_f32_e32 v174, v92
	v_add_f32_e32 v237, v157, v237
	v_add_f32_e32 v238, v173, v238
	v_exp_f32_e32 v159, v109
	v_exp_f32_e32 v175, v93
	v_add_f32_e32 v237, v158, v237
	v_add_f32_e32 v238, v174, v238
	v_exp_f32_e32 v160, v110
	v_exp_f32_e32 v176, v94
	v_add_f32_e32 v237, v159, v237
	v_add_f32_e32 v238, v175, v238
	v_exp_f32_e32 v161, v111
	v_exp_f32_e32 v177, v95
	v_add_f32_e32 v237, v160, v237
	v_add_f32_e32 v238, v176, v238
	v_exp_f32_e32 v162, v112
	v_exp_f32_e32 v178, v96
	v_add_f32_e32 v237, v161, v237
	v_add_f32_e32 v238, v177, v238
	v_exp_f32_e32 v163, v113
	v_exp_f32_e32 v179, v97
	v_add_f32_e32 v237, v162, v237
	v_add_f32_e32 v238, v178, v238
	s_nop 0
	v_add_f32_e32 v237, v163, v237
	v_add_f32_e32 v238, v179, v238
	v_add_f32_e32 v204, v237, v238
	v_cmp_lt_f32_e32 vcc, s85, v204
	s_cbranch_vccz .Lda7_pack
; __device__ __forceinline__ float swap32_max(float m) { auto rr = __builtin_amdgcn_permlane32_swap(__float_as_uint(m), __float_as_uint(m), false, false); return fmaxf(__uint_as_float(rr[0]), __uint_as_float(rr[1])); }
; #define EXPSUM_BLOCK() do { psa = 0.f; psb = 0.f; \
;             _Pragma("unroll") for (int r = 0; r < 16; ++r) { s0[r] = __builtin_amdgcn_exp2f(s0[r]); s1[r] = __builtin_amdgcn_exp2f(s1[r]); psa += s0[r]; asm("" : "+v"(psa)); psb += s1[r]; asm("" : "+v"(psb)); } } while (0)
; template <bool DIFF>
; __device__ __forceinline__ void attn_unit(const AttnP& A, int b, int h, int qi, ldsp lds) {
;     ...
;             if (full) {
;                 float ma = fmaxf(fmaxf(s0[0], s0[1]), s1[0]), mb = fmaxf(fmaxf(s0[2], s0[3]), s1[1]);
;                 ma = fmaxf(fmaxf(ma, s1[2]), s1[3]);
; #pragma unroll
;                 for (int r = 4; r < 16; r += 4) { ma = fmaxf(fmaxf(ma, s0[r]), s0[r + 1]); mb = fmaxf(fmaxf(mb, s0[r + 2]), s0[r + 3]); ma = fmaxf(fmaxf(ma, s1[r]), s1[r + 1]); mb = fmaxf(fmaxf(mb, s1[r + 2]), s1[r + 3]); }
;                 const float rm = swap32_max(fmaxf(ma, mb));
;                 const float dl = (kt == kt0) ? ((rm == -INFINITY) ? 0.f : rm) : fmaxf(rm, 0.f);
;                 mhat += dl;
; #pragma unroll
;                 for (int r = 0; r < 16; ++r) { s0[r] -= dl; s1[r] -= dl; negm[r] = -mhat; }
;                 const float f = (kt == kt0) ? 1.0f : __builtin_amdgcn_exp2f(-dl);
;                 l_run *= f;
; #pragma unroll
;                 for (int t = 0; t < NTD; ++t)
; #pragma unroll
;                     for (int r = 0; r < 16; ++r) o[t][r] *= f;
;                 EXPSUM_BLOCK();
;             }
;             l_run += psa + psb;
.Lda6_full:
	v_max_f32_e32 v204, v98, v99
	v_max3_f32 v205, v100, v101, v83
	v_max3_f32 v204, v204, v82, v84
	v_max3_f32 v204, v204, v85, v102
	v_max3_f32 v205, v205, v104, v105
	v_max3_f32 v204, v204, v103, v86
	v_max3_f32 v205, v205, v88, v89
	v_max3_f32 v204, v204, v87, v106
	v_max3_f32 v205, v205, v108, v109
	v_max3_f32 v204, v204, v107, v90
	v_max3_f32 v205, v205, v92, v93
	v_max3_f32 v204, v204, v91, v110
	v_max3_f32 v205, v205, v112, v113
	v_max3_f32 v204, v204, v111, v94
	v_max3_f32 v205, v205, v96, v97
	v_max3_f32 v204, v204, v95, v205
	v_mov_b32_e32 v205, v204
	s_nop 1
	v_permlane32_swap_b32_e32 v204, v205
	s_nop 1
	v_max_f32_e32 v204, v204, v205
	v_cmp_neq_f32_e32 vcc, s84, v204
	s_nop 1
	v_cndmask_b32_e32 v205, 0, v204, vcc
	v_max_f32_e32 v204, 0, v204
	s_nop 0
	v_cndmask_b32_e64 v205, v205, v204, s[48:49]
	v_exp_f32_e64 v204, -v205
	v_add_f32_e32 v235, v235, v205
	s_nop 0
	v_cndmask_b32_e64 v204, 1.0, v204, s[48:49]
	v_mul_f32_e32 v230, v230, v204
	v_mul_f32_e32 v2, v2, v204
	v_mul_f32_e32 v3, v3, v204
	v_mul_f32_e32 v4, v4, v204
	v_mul_f32_e32 v5, v5, v204
	v_mul_f32_e32 v6, v6, v204
	v_mul_f32_e32 v7, v7, v204
	v_mul_f32_e32 v8, v8, v204
	v_mul_f32_e32 v9, v9, v204
	v_mul_f32_e32 v10, v10, v204
	v_mul_f32_e32 v11, v11, v204
	v_mul_f32_e32 v12, v12, v204
	v_mul_f32_e32 v13, v13, v204
	v_mul_f32_e32 v14, v14, v204
	v_mul_f32_e32 v15, v15, v204
	v_mul_f32_e32 v16, v16, v204
	v_mul_f32_e32 v17, v17, v204
	v_mul_f32_e32 v18, v18, v204
	v_mul_f32_e32 v19, v19, v204
	v_mul_f32_e32 v20, v20, v204
	v_mul_f32_e32 v21, v21, v204
	v_mul_f32_e32 v22, v22, v204
	v_mul_f32_e32 v23, v23, v204
	v_mul_f32_e32 v24, v24, v204
	v_mul_f32_e32 v25, v25, v204
	v_mul_f32_e32 v26, v26, v204
	v_mul_f32_e32 v27, v27, v204
	v_mul_f32_e32 v28, v28, v204
	v_mul_f32_e32 v29, v29, v204
	v_mul_f32_e32 v30, v30, v204
	v_mul_f32_e32 v31, v31, v204
	v_mul_f32_e32 v32, v32, v204
	v_mul_f32_e32 v33, v33, v204
	v_mul_f32_e32 v34, v34, v204
	v_mul_f32_e32 v35, v35, v204
	v_mul_f32_e32 v36, v36, v204
	v_mul_f32_e32 v37, v37, v204
	v_mul_f32_e32 v38, v38, v204
	v_mul_f32_e32 v39, v39, v204
	v_mul_f32_e32 v40, v40, v204
	v_mul_f32_e32 v41, v41, v204
	v_mul_f32_e32 v42, v42, v204
	v_mul_f32_e32 v43, v43, v204
	v_mul_f32_e32 v44, v44, v204
	v_mul_f32_e32 v45, v45, v204
	v_mul_f32_e32 v46, v46, v204
	v_mul_f32_e32 v47, v47, v204
	v_mul_f32_e32 v48, v48, v204
	v_mul_f32_e32 v49, v49, v204
	v_mul_f32_e32 v50, v50, v204
	v_mul_f32_e32 v51, v51, v204
	v_mul_f32_e32 v52, v52, v204
	v_mul_f32_e32 v53, v53, v204
	v_mul_f32_e32 v54, v54, v204
	v_mul_f32_e32 v55, v55, v204
	v_mul_f32_e32 v56, v56, v204
	v_mul_f32_e32 v57, v57, v204
	v_mul_f32_e32 v58, v58, v204
	v_mul_f32_e32 v59, v59, v204
	v_mul_f32_e32 v60, v60, v204
	v_mul_f32_e32 v61, v61, v204
	v_mul_f32_e32 v62, v62, v204
	v_mul_f32_e32 v63, v63, v204
	v_mul_f32_e32 v64, v64, v204
	v_mul_f32_e32 v65, v65, v204
	v_xor_b32_e32 v66, 0x80000000, v235
	v_mov_b32_e32 v67, v66
	v_mov_b32_e32 v68, v66
	v_mov_b32_e32 v69, v66
	v_mov_b32_e32 v70, v66
	v_mov_b32_e32 v71, v66
	v_mov_b32_e32 v72, v66
	v_mov_b32_e32 v73, v66
	v_mov_b32_e32 v74, v66
	v_mov_b32_e32 v75, v66
	v_mov_b32_e32 v76, v66
	v_mov_b32_e32 v77, v66
	v_mov_b32_e32 v78, v66
	v_mov_b32_e32 v79, v66
	v_mov_b32_e32 v80, v66
	v_mov_b32_e32 v81, v66
	v_sub_f32_e32 v148, v98, v205
	v_sub_f32_e32 v164, v82, v205
	v_sub_f32_e32 v149, v99, v205
	v_sub_f32_e32 v165, v83, v205
	v_sub_f32_e32 v150, v100, v205
	v_sub_f32_e32 v166, v84, v205
	v_sub_f32_e32 v151, v101, v205
	v_sub_f32_e32 v167, v85, v205
	v_sub_f32_e32 v152, v102, v205
	v_sub_f32_e32 v168, v86, v205
	v_sub_f32_e32 v153, v103, v205
	v_sub_f32_e32 v169, v87, v205
	v_sub_f32_e32 v154, v104, v205
	v_sub_f32_e32 v170, v88, v205
	v_sub_f32_e32 v155, v105, v205
	v_sub_f32_e32 v171, v89, v205
	v_sub_f32_e32 v156, v106, v205
	v_sub_f32_e32 v172, v90, v205
	v_sub_f32_e32 v157, v107, v205
	v_sub_f32_e32 v173, v91, v205
	v_sub_f32_e32 v158, v108, v205
	v_sub_f32_e32 v174, v92, v205
	v_sub_f32_e32 v159, v109, v205
	v_sub_f32_e32 v175, v93, v205
	v_sub_f32_e32 v160, v110, v205
	v_sub_f32_e32 v176, v94, v205
	v_sub_f32_e32 v161, v111, v205
	v_sub_f32_e32 v177, v95, v205
	v_sub_f32_e32 v162, v112, v205
	v_sub_f32_e32 v178, v96, v205
	v_sub_f32_e32 v163, v113, v205
	v_sub_f32_e32 v179, v97, v205
	v_exp_f32_e32 v148, v148
	v_exp_f32_e32 v164, v164
	v_exp_f32_e32 v149, v149
	v_exp_f32_e32 v165, v165
	v_add_f32_e32 v237, 0, v148
	v_add_f32_e32 v238, 0, v164
	v_exp_f32_e32 v150, v150
	v_exp_f32_e32 v166, v166
	v_add_f32_e32 v237, v149, v237
	v_add_f32_e32 v238, v165, v238
	v_exp_f32_e32 v151, v151
	v_exp_f32_e32 v167, v167
	v_add_f32_e32 v237, v150, v237
	v_add_f32_e32 v238, v166, v238
	v_exp_f32_e32 v152, v152
	v_exp_f32_e32 v168, v168
	v_add_f32_e32 v237, v151, v237
	v_add_f32_e32 v238, v167, v238
	v_exp_f32_e32 v153, v153
	v_exp_f32_e32 v169, v169
	v_add_f32_e32 v237, v152, v237
	v_add_f32_e32 v238, v168, v238
	v_exp_f32_e32 v154, v154
	v_exp_f32_e32 v170, v170
	v_add_f32_e32 v237, v153, v237
	v_add_f32_e32 v238, v169, v238
	v_exp_f32_e32 v155, v155
	v_exp_f32_e32 v171, v171
	v_add_f32_e32 v237, v154, v237
	v_add_f32_e32 v238, v170, v238
	v_exp_f32_e32 v156, v156
	v_exp_f32_e32 v172, v172
	v_add_f32_e32 v237, v155, v237
	v_add_f32_e32 v238, v171, v238
	v_exp_f32_e32 v157, v157
	v_exp_f32_e32 v173, v173
	v_add_f32_e32 v237, v156, v237
	v_add_f32_e32 v238, v172, v238
	v_exp_f32_e32 v158, v158
	v_exp_f32_e32 v174, v174
	v_add_f32_e32 v237, v157, v237
	v_add_f32_e32 v238, v173, v238
	v_exp_f32_e32 v159, v159
	v_exp_f32_e32 v175, v175
	v_add_f32_e32 v237, v158, v237
	v_add_f32_e32 v238, v174, v238
	v_exp_f32_e32 v160, v160
	v_exp_f32_e32 v176, v176
	v_add_f32_e32 v237, v159, v237
	v_add_f32_e32 v238, v175, v238
	v_exp_f32_e32 v161, v161
	v_exp_f32_e32 v177, v177
	v_add_f32_e32 v237, v160, v237
	v_add_f32_e32 v238, v176, v238
	v_exp_f32_e32 v162, v162
	v_exp_f32_e32 v178, v178
	v_add_f32_e32 v237, v161, v237
	v_add_f32_e32 v238, v177, v238
	v_exp_f32_e32 v163, v163
	v_exp_f32_e32 v179, v179
	v_add_f32_e32 v237, v162, v237
	v_add_f32_e32 v238, v178, v238
	s_nop 0
	v_add_f32_e32 v237, v163, v237
	v_add_f32_e32 v238, v179, v238
; __device__ __forceinline__ unsigned cvtpk(float lo, float hi) { f32x2 v = {lo, hi}; bf16x2_t b = __builtin_convertvector(v, bf16x2_t); return __builtin_bit_cast(unsigned, b); }
; __device__ __forceinline__ s16x4 vtr(ldsp p) { return __builtin_bit_cast(s16x4, __builtin_amdgcn_ds_read_tr16_b64_v4i16((LAS v4i16_t*)p)); }
; template <bool DIFF>
; __device__ __forceinline__ void attn_unit(const AttnP& A, int b, int h, int qi, ldsp lds) {
;     ...
;             bf16x8 pw[4];
; #pragma unroll
;             for (int j = 0; j < 4; ++j) {
;                 u32x4 pk;
;                 if (j < 2) { const int rb = 8 * (j & 1); pk.x = cvtpk(s0[rb], s0[rb + 1]); pk.y = cvtpk(s0[rb + 2], s0[rb + 3]); pk.z = cvtpk(s0[rb + 4], s0[rb + 5]); pk.w = cvtpk(s0[rb + 6], s0[rb + 7]); }
;                 else { const int rb = 8 * (j & 1); pk.x = cvtpk(s1[rb], s1[rb + 1]); pk.y = cvtpk(s1[rb + 2], s1[rb + 3]); pk.z = cvtpk(s1[rb + 4], s1[rb + 5]); pk.w = cvtpk(s1[rb + 6], s1[rb + 7]); }
;                 pw[j] = __builtin_bit_cast(bf16x8, pk);
;             }
;             __builtin_amdgcn_sched_barrier(0);
;             __builtin_amdgcn_s_setprio(1);
; #pragma unroll
;             for (int t = 0; t < 2; ++t)
; #pragma unroll
;                 for (int j = 0; j < 4; ++j) {
;                     const bf16x8 vf = (bf16x8){vlo[t * 4 + j][0], vlo[t * 4 + j][1], vlo[t * 4 + j][2], vlo[t * 4 + j][3], vhi[t * 4 + j][0], vhi[t * 4 + j][1], vhi[t * 4 + j][2], vhi[t * 4 + j][3]};
;                     o[t] = __builtin_amdgcn_mfma_f32_32x32x16_bf16(vf, pw[j], o[t], 0, 0, 0);
;                 }
;             if (DIFF) {
; #pragma unroll
;                 for (int t = 2; t < NTD; ++t)
; #pragma unroll
;                     for (int j = 0; j < 4; ++j) { vlo[(t - 2) * 4 + j] = vtr(Vb + trb + (16 * j) * VP + t * 64); vhi[(t - 2) * 4 + j] = vtr(Vb + trb + (16 * j + 8) * VP + t * 64); }
;                 __builtin_amdgcn_sched_barrier(0);
; #pragma unroll
;                 for (int t = 2; t < NTD; ++t)
; #pragma unroll
;                     for (int j = 0; j < 4; ++j) {
;                         const int i = (t - 2) * 4 + j;
;                         const bf16x8 vf = (bf16x8){vlo[i][0], vlo[i][1], vlo[i][2], vlo[i][3], vhi[i][0], vhi[i][1], vhi[i][2], vhi[i][3]};
;                         o[t] = __builtin_amdgcn_mfma_f32_32x32x16_bf16(vf, pw[j], o[t], 0, 0, 0);
;                     }
;             }
.Lda7_pack:
	v_add_f32_e32 v204, v238, v237
	v_cvt_pk_bf16_f32 v98, v148, v149
	v_cvt_pk_bf16_f32 v99, v150, v151
	v_cvt_pk_bf16_f32 v100, v152, v153
	v_cvt_pk_bf16_f32 v101, v154, v155
	v_cvt_pk_bf16_f32 v102, v156, v157
	v_cvt_pk_bf16_f32 v103, v158, v159
	v_cvt_pk_bf16_f32 v104, v160, v161
	v_cvt_pk_bf16_f32 v105, v162, v163
	v_cvt_pk_bf16_f32 v82, v164, v165
	v_cvt_pk_bf16_f32 v83, v166, v167
	v_cvt_pk_bf16_f32 v84, v168, v169
	v_cvt_pk_bf16_f32 v85, v170, v171
	v_cvt_pk_bf16_f32 v86, v172, v173
	v_cvt_pk_bf16_f32 v87, v174, v175
	v_cvt_pk_bf16_f32 v88, v176, v177
	v_cvt_pk_bf16_f32 v89, v178, v179
	v_add_f32_e32 v230, v204, v230
	s_branch .Lda_end
.Lda_first:
	v_add_u32_e32 v239, s45, v234
	ds_read_b128 v[148:151], v239
	ds_read_b128 v[152:155], v239 offset:8704
	ds_read_b128 v[156:159], v239 offset:32
	ds_read_b128 v[160:163], v239 offset:8736
	ds_read_b128 v[164:167], v239 offset:64
	ds_read_b128 v[168:171], v239 offset:8768
	ds_read_b128 v[172:175], v239 offset:96
	ds_read_b128 v[176:179], v239 offset:8800
	s_waitcnt lgkmcnt(7)
	v_mfma_f32_32x32x16_bf16 v[98:113], v[148:151], v[116:119], v[66:81]
	s_waitcnt lgkmcnt(6)
	v_mfma_f32_32x32x16_bf16 v[82:97], v[152:155], v[116:119], v[66:81]
	s_waitcnt lgkmcnt(5)
	v_mfma_f32_32x32x16_bf16 v[98:113], v[156:159], v[120:123], v[98:113]
	s_waitcnt lgkmcnt(4)
	v_mfma_f32_32x32x16_bf16 v[82:97], v[160:163], v[120:123], v[82:97]
	s_waitcnt lgkmcnt(3)
	v_mfma_f32_32x32x16_bf16 v[98:113], v[164:167], v[124:127], v[98:113]
	s_waitcnt lgkmcnt(2)
	v_mfma_f32_32x32x16_bf16 v[82:97], v[168:171], v[124:127], v[82:97]
	s_waitcnt lgkmcnt(1)
	v_mfma_f32_32x32x16_bf16 v[98:113], v[172:175], v[128:131], v[98:113]
	s_waitcnt lgkmcnt(0)
	v_mfma_f32_32x32x16_bf16 v[82:97], v[176:179], v[128:131], v[82:97]
	s_branch .Lda_postqk
.Lda_last:
	v_add_u32_e32 v239, s45, v234
	v_add_u32_e32 v236, s71, v231
	ds_read_b64_tr_b16 v[148:149], v236 offset:17472
	ds_read_b64_tr_b16 v[150:151], v236 offset:20032
	ds_read_b64_tr_b16 v[152:153], v236 offset:17408
	ds_read_b64_tr_b16 v[154:155], v236 offset:19968
	ds_read_b64_tr_b16 v[156:157], v236 offset:22592
	ds_read_b64_tr_b16 v[158:159], v236 offset:25152
	ds_read_b64_tr_b16 v[160:161], v236 offset:22528
	ds_read_b64_tr_b16 v[162:163], v236 offset:25088
	ds_read_b64_tr_b16 v[164:165], v236 offset:27712
	ds_read_b64_tr_b16 v[166:167], v236 offset:30272
	ds_read_b64_tr_b16 v[168:169], v236 offset:27648
	ds_read_b64_tr_b16 v[170:171], v236 offset:30208
	ds_read_b64_tr_b16 v[172:173], v236 offset:32768
	ds_read_b64_tr_b16 v[174:175], v236 offset:35328
	ds_read_b64_tr_b16 v[176:177], v236 offset:32832
	ds_read_b64_tr_b16 v[178:179], v236 offset:35392
	s_waitcnt lgkmcnt(14)
	v_mfma_f32_32x32x16_bf16 v[34:49], v[148:151], v[98:101], v[34:49]
	ds_read_b64_tr_b16 v[90:91], v236 offset:17536
	ds_read_b64_tr_b16 v[92:93], v236 offset:20096
	s_waitcnt lgkmcnt(14)
	v_mfma_f32_32x32x16_bf16 v[50:65], v[152:155], v[98:101], v[50:65]
	ds_read_b64_tr_b16 v[94:95], v236 offset:17600
	ds_read_b64_tr_b16 v[96:97], v236 offset:20160
	s_waitcnt lgkmcnt(14)
	v_mfma_f32_32x32x16_bf16 v[34:49], v[156:159], v[102:105], v[34:49]
	ds_read_b64_tr_b16 v[106:107], v236 offset:22656
	ds_read_b64_tr_b16 v[108:109], v236 offset:25216
	s_waitcnt lgkmcnt(14)
	v_mfma_f32_32x32x16_bf16 v[50:65], v[160:163], v[102:105], v[50:65]
	ds_read_b64_tr_b16 v[110:111], v236 offset:22720
	ds_read_b64_tr_b16 v[112:113], v236 offset:25280
	s_waitcnt lgkmcnt(14)
	v_mfma_f32_32x32x16_bf16 v[34:49], v[164:167], v[82:85], v[34:49]
	ds_read_b64_tr_b16 v[240:241], v236 offset:27776
	ds_read_b64_tr_b16 v[242:243], v236 offset:30336
	s_waitcnt lgkmcnt(14)
	v_mfma_f32_32x32x16_bf16 v[50:65], v[168:171], v[82:85], v[50:65]
	ds_read_b64_tr_b16 v[148:149], v236 offset:27840
	ds_read_b64_tr_b16 v[150:151], v236 offset:30400
	s_waitcnt lgkmcnt(14)
	v_mfma_f32_32x32x16_bf16 v[50:65], v[172:175], v[86:89], v[50:65]
	ds_read_b64_tr_b16 v[152:153], v236 offset:32896
	ds_read_b64_tr_b16 v[154:155], v236 offset:35456
	s_waitcnt lgkmcnt(14)
	v_mfma_f32_32x32x16_bf16 v[34:49], v[176:179], v[86:89], v[34:49]
	ds_read_b64_tr_b16 v[156:157], v236 offset:32960
	ds_read_b64_tr_b16 v[158:159], v236 offset:35520
	s_waitcnt lgkmcnt(14)
	v_mfma_f32_32x32x16_bf16 v[18:33], v[90:93], v[98:101], v[18:33]
	s_waitcnt lgkmcnt(12)
	v_mfma_f32_32x32x16_bf16 v[2:17], v[94:97], v[98:101], v[2:17]
	s_waitcnt lgkmcnt(10)
	v_mfma_f32_32x32x16_bf16 v[18:33], v[106:109], v[102:105], v[18:33]
	s_waitcnt lgkmcnt(8)
	v_mfma_f32_32x32x16_bf16 v[2:17], v[110:113], v[102:105], v[2:17]
	s_waitcnt lgkmcnt(6)
	v_mfma_f32_32x32x16_bf16 v[18:33], v[240:243], v[82:85], v[18:33]
	s_waitcnt lgkmcnt(4)
	v_mfma_f32_32x32x16_bf16 v[2:17], v[148:151], v[82:85], v[2:17]
	s_waitcnt lgkmcnt(2)
	v_mfma_f32_32x32x16_bf16 v[18:33], v[152:155], v[86:89], v[18:33]
	s_waitcnt lgkmcnt(0)
	v_mfma_f32_32x32x16_bf16 v[2:17], v[156:159], v[86:89], v[2:17]

; template <bool DIFF>
; __device__ __forceinline__ void attn_unit(const AttnP& A, int b, int h, int qi, ldsp lds) {
;     ...
;         if (kt + 1 < nt) STORE_TILE((kt + 1) & 1);
;         __syncthreads();
;     }
.Lda8_snov:
.Lda_end:
	s_waitcnt lgkmcnt(0)
	s_barrier
	s_add_i32 s75, s75, 1
	s_add_i32 s74, s74, 64
	s_cmp_le_i32 s75, s31
	s_cbranch_scc1 .Lda_top
	s_branch .LBB0_515

; __device__ __forceinline__ s16x4 vtr(ldsp p) { return __builtin_bit_cast(s16x4, __builtin_amdgcn_ds_read_tr16_b64_v4i16((LAS v4i16_t*)p)); }
; #define MASK_BLOCK() do { if (kt == 0 || kt >= diag0) { \
;             _Pragma("unroll") for (int r = 0; r < 16; ++r) { const int kpp = 64 * kt + crow(r, hi); \
;                 if (kpp < 48 || kpp > q_pp) s0[r] = -INFINITY; \
;                 if (kpp + 32 < 48 || kpp + 32 > q_pp) s1[r] = -INFINITY; } } } while (0)
; #define EXPSUM_BLOCK() do { psa = 0.f; psb = 0.f; \
;             _Pragma("unroll") for (int r = 0; r < 16; ++r) { s0[r] = __builtin_amdgcn_exp2f(s0[r]); s1[r] = __builtin_amdgcn_exp2f(s1[r]); psa += s0[r]; asm("" : "+v"(psa)); psb += s1[r]; asm("" : "+v"(psb)); } } while (0)
; template <bool DIFF>
; __device__ __forceinline__ void attn_unit(const AttnP& A, int b, int h, int qi, ldsp lds) {
;     ...
;             QK_BLOCK();
;             s16x4 vlo[8], vhi[8];
; #pragma unroll
;             for (int t = 0; t < 2; ++t)
; #pragma unroll
;                 for (int j = 0; j < 4; ++j) { vlo[t * 4 + j] = vtr(Vb + trb + (16 * j) * VP + t * 64); vhi[t * 4 + j] = vtr(Vb + trb + (16 * j + 8) * VP + t * 64); }
;             __builtin_amdgcn_sched_barrier(0);
;             MASK_BLOCK();
;             bool full = (kt == kt0);
;             float psa, psb;
;             if (!full) {
;                 EXPSUM_BLOCK();
;                 if (__any(psa + psb > 1.0e18f)) { full = true; QK_BLOCK();
; #pragma unroll
;                     for (int t = 0; t < 2; ++t)
; #pragma unroll
;                         for (int j = 0; j < 4; ++j) { vlo[t * 4 + j] = vtr(Vb + trb + (16 * j) * VP + t * 64); vhi[t * 4 + j] = vtr(Vb + trb + (16 * j + 8) * VP + t * 64); }
;                     MASK_BLOCK(); }
;             }
.Lda11_nok:
	s_cmp_eq_u32 s75, 0
	s_cbranch_scc1 .Ldb_first
	s_cmp_gt_i32 s75, s44
	s_cbranch_scc1 .Ldb_stores
	s_add_i32 s73, s74, -64
	s_cmp_eq_u32 s73, 0
	s_cselect_b64 s[40:41], -1, 0
	s_cselect_b64 s[48:49], 0, -1
	s_lshr_b32 s0, s73, 6
	s_cmp_ge_i32 s0, s72
	s_cselect_b64 s[46:47], -1, 0
	s_or_b64 s[46:47], s[46:47], s[40:41]
	s_or_b64 s[46:47], s[46:47], s[24:25]
	s_and_b64 vcc, exec, s[46:47]
	s_cbranch_vccz .Lda12_nomask
	v_add_u32_e32 v204, s73, v115
	v_cmp_gt_i32_e32 vcc, v204, v192
	s_or_b64 vcc, s[40:41], vcc
	v_add_u32_e32 v205, 32, v204
	v_cndmask_b32_e32 v98, v98, v223, vcc
	v_cmp_gt_i32_e32 vcc, v205, v192
	s_or_b64 vcc, s[40:41], vcc
	v_add_u32_e32 v205, 33, v204
	v_cndmask_b32_e32 v82, v82, v223, vcc
	v_cmp_ge_i32_e32 vcc, v204, v192
	s_or_b64 vcc, s[40:41], vcc
	s_nop 0
	v_cndmask_b32_e32 v99, v99, v223, vcc
	v_cmp_gt_i32_e32 vcc, v205, v192
	s_or_b64 vcc, s[40:41], vcc
	v_add_u32_e32 v205, 2, v204
	v_cndmask_b32_e32 v83, v83, v223, vcc
	v_cmp_gt_i32_e32 vcc, v205, v192
	s_or_b64 vcc, s[40:41], vcc
	v_add_u32_e32 v205, 34, v204
	v_cndmask_b32_e32 v100, v100, v223, vcc
	v_cmp_gt_i32_e32 vcc, v205, v192
	s_or_b64 vcc, s[40:41], vcc
	v_add_u32_e32 v205, 3, v204
	v_cndmask_b32_e32 v84, v84, v223, vcc
	v_cmp_gt_i32_e32 vcc, v205, v192
	s_or_b64 vcc, s[40:41], vcc
	v_add_u32_e32 v205, 35, v204
	v_cndmask_b32_e32 v101, v101, v223, vcc
	v_cmp_gt_i32_e32 vcc, v205, v192
	s_or_b64 vcc, s[40:41], vcc
	v_add_u32_e32 v205, 8, v204
	v_cndmask_b32_e32 v85, v85, v223, vcc
	v_cmp_gt_i32_e32 vcc, v205, v192
	s_or_b64 vcc, s[40:41], vcc
	v_add_u32_e32 v205, 40, v204
	v_cndmask_b32_e32 v102, v102, v223, vcc
	v_cmp_gt_i32_e32 vcc, v205, v192
	s_or_b64 vcc, s[40:41], vcc
	v_add_u32_e32 v205, 9, v204
	v_cndmask_b32_e32 v86, v86, v223, vcc
	v_cmp_gt_i32_e32 vcc, v205, v192
	s_or_b64 vcc, s[40:41], vcc
	v_add_u32_e32 v205, 41, v204
	v_cndmask_b32_e32 v103, v103, v223, vcc
	v_cmp_gt_i32_e32 vcc, v205, v192
	s_or_b64 vcc, s[40:41], vcc
	v_add_u32_e32 v205, 10, v204
	v_cndmask_b32_e32 v87, v87, v223, vcc
	v_cmp_gt_i32_e32 vcc, v205, v192
	s_or_b64 vcc, s[40:41], vcc
	v_add_u32_e32 v205, 42, v204
	v_cndmask_b32_e32 v104, v104, v223, vcc
	v_cmp_gt_i32_e32 vcc, v205, v192
	s_or_b64 vcc, s[40:41], vcc
	v_add_u32_e32 v205, 11, v204
	v_cndmask_b32_e32 v88, v88, v223, vcc
	v_cmp_gt_i32_e32 vcc, v205, v192
	s_or_b64 vcc, s[40:41], vcc
	v_add_u32_e32 v205, 43, v204
	v_cndmask_b32_e32 v105, v105, v223, vcc
	v_cmp_gt_i32_e32 vcc, v205, v192
	s_or_b64 vcc, s[40:41], vcc
	v_add_u32_e32 v205, 16, v204
	v_cndmask_b32_e32 v89, v89, v223, vcc
	v_cmp_gt_u32_e32 vcc, 48, v205
	v_cmp_gt_i32_e64 s[46:47], v205, v192
	s_or_b64 vcc, vcc, s[46:47]
	v_add_u32_e32 v205, 48, v204
	v_cndmask_b32_e32 v106, v106, v223, vcc
	v_cmp_le_i32_e32 vcc, v205, v192
	v_add_u32_e32 v205, 17, v204
	v_cmp_gt_i32_e64 s[46:47], v205, v192
	v_cndmask_b32_e32 v90, v223, v90, vcc
	v_cmp_gt_u32_e32 vcc, 48, v205
	s_or_b64 vcc, vcc, s[46:47]
	v_add_u32_e32 v205, 49, v204
	v_cndmask_b32_e32 v107, v107, v223, vcc
	v_cmp_le_i32_e32 vcc, v205, v192
	v_add_u32_e32 v205, 18, v204
	v_cmp_gt_i32_e64 s[46:47], v205, v192
	v_cndmask_b32_e32 v91, v223, v91, vcc
	v_cmp_gt_u32_e32 vcc, 48, v205
	s_or_b64 vcc, vcc, s[46:47]
	v_add_u32_e32 v205, 50, v204
	v_cndmask_b32_e32 v108, v108, v223, vcc
	v_cmp_le_i32_e32 vcc, v205, v192
	v_add_u32_e32 v205, 19, v204
	v_cmp_gt_i32_e64 s[46:47], v205, v192
	v_cndmask_b32_e32 v92, v223, v92, vcc
	v_cmp_gt_u32_e32 vcc, 48, v205
	s_or_b64 vcc, vcc, s[46:47]
	v_add_u32_e32 v205, 51, v204
	v_cndmask_b32_e32 v109, v109, v223, vcc
	v_cmp_le_i32_e32 vcc, v205, v192
	v_add_u32_e32 v205, 24, v204
	v_cmp_gt_i32_e64 s[46:47], v205, v192
	v_cndmask_b32_e32 v93, v223, v93, vcc
	v_cmp_gt_u32_e32 vcc, 48, v205
	s_or_b64 vcc, vcc, s[46:47]
	v_add_u32_e32 v205, 56, v204
	v_cndmask_b32_e32 v110, v110, v223, vcc
	v_cmp_le_i32_e32 vcc, v205, v192
	v_add_u32_e32 v205, 25, v204
	v_cmp_gt_i32_e64 s[46:47], v205, v192
	v_cndmask_b32_e32 v94, v223, v94, vcc
	v_cmp_gt_u32_e32 vcc, 48, v205
	s_or_b64 vcc, vcc, s[46:47]
	v_add_u32_e32 v205, 57, v204
	v_cndmask_b32_e32 v111, v111, v223, vcc
	v_cmp_le_i32_e32 vcc, v205, v192
	v_add_u32_e32 v205, 26, v204
	v_cmp_gt_i32_e64 s[46:47], v205, v192
	v_cndmask_b32_e32 v95, v223, v95, vcc
	v_cmp_gt_u32_e32 vcc, 48, v205
	s_or_b64 vcc, vcc, s[46:47]
	v_add_u32_e32 v205, 58, v204
	v_cndmask_b32_e32 v112, v112, v223, vcc
	v_cmp_le_i32_e32 vcc, v205, v192
	v_add_u32_e32 v205, 27, v204
	v_cmp_gt_i32_e64 s[46:47], v205, v192
	v_cndmask_b32_e32 v96, v223, v96, vcc
	v_cmp_gt_u32_e32 vcc, 48, v205
	s_or_b64 vcc, vcc, s[46:47]
	v_add_u32_e32 v204, 59, v204
	v_cndmask_b32_e32 v113, v113, v223, vcc
	v_cmp_le_i32_e32 vcc, v204, v192
	s_nop 1
	v_cndmask_b32_e32 v97, v223, v97, vcc

; __device__ __forceinline__ unsigned cvtpk(float lo, float hi) { f32x2 v = {lo, hi}; bf16x2_t b = __builtin_convertvector(v, bf16x2_t); return __builtin_bit_cast(unsigned, b); }
; __device__ __forceinline__ s16x4 vtr(ldsp p) { return __builtin_bit_cast(s16x4, __builtin_amdgcn_ds_read_tr16_b64_v4i16((LAS v4i16_t*)p)); }
; template <bool DIFF>
; __device__ __forceinline__ void attn_unit(const AttnP& A, int b, int h, int qi, ldsp lds) {
;     ...
;             bf16x8 pw[4];
; #pragma unroll
;             for (int j = 0; j < 4; ++j) {
;                 u32x4 pk;
;                 if (j < 2) { const int rb = 8 * (j & 1); pk.x = cvtpk(s0[rb], s0[rb + 1]); pk.y = cvtpk(s0[rb + 2], s0[rb + 3]); pk.z = cvtpk(s0[rb + 4], s0[rb + 5]); pk.w = cvtpk(s0[rb + 6], s0[rb + 7]); }
;                 else { const int rb = 8 * (j & 1); pk.x = cvtpk(s1[rb], s1[rb + 1]); pk.y = cvtpk(s1[rb + 2], s1[rb + 3]); pk.z = cvtpk(s1[rb + 4], s1[rb + 5]); pk.w = cvtpk(s1[rb + 6], s1[rb + 7]); }
;                 pw[j] = __builtin_bit_cast(bf16x8, pk);
;             }
;             __builtin_amdgcn_sched_barrier(0);
;             __builtin_amdgcn_s_setprio(1);
; #pragma unroll
;             for (int t = 0; t < 2; ++t)
; #pragma unroll
;                 for (int j = 0; j < 4; ++j) {
;                     const bf16x8 vf = (bf16x8){vlo[t * 4 + j][0], vlo[t * 4 + j][1], vlo[t * 4 + j][2], vlo[t * 4 + j][3], vhi[t * 4 + j][0], vhi[t * 4 + j][1], vhi[t * 4 + j][2], vhi[t * 4 + j][3]};
;                     o[t] = __builtin_amdgcn_mfma_f32_32x32x16_bf16(vf, pw[j], o[t], 0, 0, 0);
;                 }
;             if (DIFF) {
; #pragma unroll
;                 for (int t = 2; t < NTD; ++t)
; #pragma unroll
;                     for (int j = 0; j < 4; ++j) { vlo[(t - 2) * 4 + j] = vtr(Vb + trb + (16 * j) * VP + t * 64); vhi[(t - 2) * 4 + j] = vtr(Vb + trb + (16 * j + 8) * VP + t * 64); }
;                 __builtin_amdgcn_sched_barrier(0);
; #pragma unroll
;                 for (int t = 2; t < NTD; ++t)
; #pragma unroll
;                     for (int j = 0; j < 4; ++j) {
;                         const int i = (t - 2) * 4 + j;
;                         const bf16x8 vf = (bf16x8){vlo[i][0], vlo[i][1], vlo[i][2], vlo[i][3], vhi[i][0], vhi[i][1], vhi[i][2], vhi[i][3]};
;                         o[t] = __builtin_amdgcn_mfma_f32_32x32x16_bf16(vf, pw[j], o[t], 0, 0, 0);
;                     }
;             }
.Lda14_pack:
	v_add_u32_e32 v239, s45, v234
	v_add_u32_e32 v236, s71, v231
	ds_read_b64_tr_b16 v[90:91], v236 offset:17472
	ds_read_b64_tr_b16 v[92:93], v236 offset:20032
	ds_read_b64_tr_b16 v[94:95], v236 offset:17408
	ds_read_b64_tr_b16 v[96:97], v236 offset:19968
	ds_read_b64_tr_b16 v[106:107], v236 offset:22592
	ds_read_b64_tr_b16 v[108:109], v236 offset:25152
	ds_read_b64_tr_b16 v[110:111], v236 offset:22528
	ds_read_b64_tr_b16 v[112:113], v236 offset:25088
	ds_read_b64_tr_b16 v[240:241], v236 offset:27712
	ds_read_b64_tr_b16 v[242:243], v236 offset:30272
	v_add_f32_e32 v204, v238, v237
	v_cvt_pk_bf16_f32 v98, v148, v149
	v_cvt_pk_bf16_f32 v99, v150, v151
	v_cvt_pk_bf16_f32 v100, v152, v153
	v_cvt_pk_bf16_f32 v101, v154, v155
	v_cvt_pk_bf16_f32 v102, v156, v157
	v_cvt_pk_bf16_f32 v103, v158, v159
	v_cvt_pk_bf16_f32 v104, v160, v161
	v_cvt_pk_bf16_f32 v105, v162, v163
	v_cvt_pk_bf16_f32 v82, v164, v165
	v_cvt_pk_bf16_f32 v83, v166, v167
	v_cvt_pk_bf16_f32 v84, v168, v169
	v_cvt_pk_bf16_f32 v85, v170, v171
	v_cvt_pk_bf16_f32 v86, v172, v173
	v_cvt_pk_bf16_f32 v87, v174, v175
	v_cvt_pk_bf16_f32 v88, v176, v177
	v_cvt_pk_bf16_f32 v89, v178, v179
	v_add_f32_e32 v230, v204, v230
	ds_read_b64_tr_b16 v[148:149], v236 offset:27648
	ds_read_b64_tr_b16 v[150:151], v236 offset:30208
	ds_read_b64_tr_b16 v[152:153], v236 offset:32768
	ds_read_b64_tr_b16 v[154:155], v236 offset:35328
	ds_read_b64_tr_b16 v[156:157], v236 offset:32832
	ds_read_b64_tr_b16 v[158:159], v236 offset:35392
	s_cmp_eq_u32 s75, s44
	s_cbranch_scc1 .Ldb_last
	s_waitcnt lgkmcnt(14)
	v_mfma_f32_32x32x16_bf16 v[34:49], v[90:93], v[98:101], v[34:49]
	ds_read_b64_tr_b16 v[160:161], v236 offset:17536
	ds_read_b64_tr_b16 v[162:163], v236 offset:20096
	s_waitcnt lgkmcnt(14)
	v_mfma_f32_32x32x16_bf16 v[50:65], v[94:97], v[98:101], v[50:65]
	ds_read_b64_tr_b16 v[164:165], v236 offset:17600
	ds_read_b64_tr_b16 v[166:167], v236 offset:20160
	s_waitcnt lgkmcnt(14)
	v_mfma_f32_32x32x16_bf16 v[34:49], v[106:109], v[102:105], v[34:49]
	ds_read_b64_tr_b16 v[168:169], v236 offset:22656
	ds_read_b64_tr_b16 v[170:171], v236 offset:25216
	s_waitcnt lgkmcnt(14)
	v_mfma_f32_32x32x16_bf16 v[50:65], v[110:113], v[102:105], v[50:65]
	ds_read_b64_tr_b16 v[172:173], v236 offset:22720
	ds_read_b64_tr_b16 v[174:175], v236 offset:25280
	s_waitcnt lgkmcnt(14)
	v_mfma_f32_32x32x16_bf16 v[34:49], v[240:243], v[82:85], v[34:49]
	ds_read_b64_tr_b16 v[176:177], v236 offset:27776
	ds_read_b64_tr_b16 v[178:179], v236 offset:30336
	s_waitcnt lgkmcnt(14)
	v_mfma_f32_32x32x16_bf16 v[50:65], v[148:151], v[82:85], v[50:65]
	ds_read_b64_tr_b16 v[90:91], v236 offset:27840
	ds_read_b64_tr_b16 v[92:93], v236 offset:30400
	s_waitcnt lgkmcnt(14)
	v_mfma_f32_32x32x16_bf16 v[50:65], v[152:155], v[86:89], v[50:65]
	ds_read_b64_tr_b16 v[94:95], v236 offset:32896
	ds_read_b64_tr_b16 v[96:97], v236 offset:35456
	s_waitcnt lgkmcnt(14)
	v_mfma_f32_32x32x16_bf16 v[34:49], v[156:159], v[86:89], v[34:49]
	ds_read_b64_tr_b16 v[106:107], v236 offset:32960
	ds_read_b64_tr_b16 v[108:109], v236 offset:35520
	s_waitcnt lgkmcnt(14)
	v_mfma_f32_32x32x16_bf16 v[18:33], v[160:163], v[98:101], v[18:33]
	ds_read_b128 v[240:243], v239
	s_waitcnt lgkmcnt(13)
	v_mfma_f32_32x32x16_bf16 v[2:17], v[164:167], v[98:101], v[2:17]
	ds_read_b128 v[148:151], v239 offset:8704
	s_waitcnt lgkmcnt(12)
	v_mfma_f32_32x32x16_bf16 v[18:33], v[168:171], v[102:105], v[18:33]
	ds_read_b128 v[152:155], v239 offset:32
	s_waitcnt lgkmcnt(11)
	v_mfma_f32_32x32x16_bf16 v[2:17], v[172:175], v[102:105], v[2:17]
	ds_read_b128 v[156:159], v239 offset:8736
	s_waitcnt lgkmcnt(10)
	v_mfma_f32_32x32x16_bf16 v[18:33], v[176:179], v[82:85], v[18:33]
	ds_read_b128 v[160:163], v239 offset:64
	s_waitcnt lgkmcnt(9)
	v_mfma_f32_32x32x16_bf16 v[2:17], v[90:93], v[82:85], v[2:17]
	ds_read_b128 v[164:167], v239 offset:8768
	s_waitcnt lgkmcnt(8)
	v_mfma_f32_32x32x16_bf16 v[18:33], v[94:97], v[86:89], v[18:33]
	ds_read_b128 v[168:171], v239 offset:96
	s_waitcnt lgkmcnt(7)
	v_mfma_f32_32x32x16_bf16 v[2:17], v[106:109], v[86:89], v[2:17]
	ds_read_b128 v[172:175], v239 offset:8800
	s_waitcnt lgkmcnt(7)
	v_mfma_f32_32x32x16_bf16 v[98:113], v[240:243], v[116:119], v[66:81]
	s_waitcnt lgkmcnt(6)
	v_mfma_f32_32x32x16_bf16 v[82:97], v[148:151], v[116:119], v[66:81]
	s_waitcnt lgkmcnt(5)
	v_mfma_f32_32x32x16_bf16 v[98:113], v[152:155], v[120:123], v[98:113]
	s_waitcnt lgkmcnt(4)
	v_mfma_f32_32x32x16_bf16 v[82:97], v[156:159], v[120:123], v[82:97]
	s_waitcnt lgkmcnt(3)
	v_mfma_f32_32x32x16_bf16 v[98:113], v[160:163], v[124:127], v[98:113]
	s_waitcnt lgkmcnt(2)
	v_mfma_f32_32x32x16_bf16 v[82:97], v[164:167], v[124:127], v[82:97]
	s_waitcnt lgkmcnt(1)
	v_mfma_f32_32x32x16_bf16 v[98:113], v[168:171], v[128:131], v[98:113]
	s_waitcnt lgkmcnt(0)
	v_mfma_f32_32x32x16_bf16 v[82:97], v[172:175], v[128:131], v[82:97]
	s_branch .Ldb_stores
; __device__ __forceinline__ s16x4 vtr(ldsp p) { return __builtin_bit_cast(s16x4, __builtin_amdgcn_ds_read_tr16_b64_v4i16((LAS v4i16_t*)p)); }
; template <bool DIFF>
; __device__ __forceinline__ void attn_unit(const AttnP& A, int b, int h, int qi, ldsp lds) {
;     ...
; #pragma unroll
;             for (int t = 0; t < 2; ++t)
; #pragma unroll
;                 for (int j = 0; j < 4; ++j) {
;                     const bf16x8 vf = (bf16x8){vlo[t * 4 + j][0], vlo[t * 4 + j][1], vlo[t * 4 + j][2], vlo[t * 4 + j][3], vhi[t * 4 + j][0], vhi[t * 4 + j][1], vhi[t * 4 + j][2], vhi[t * 4 + j][3]};
;                     o[t] = __builtin_amdgcn_mfma_f32_32x32x16_bf16(vf, pw[j], o[t], 0, 0, 0);
;                 }
;             if (DIFF) {
; #pragma unroll
;                 for (int t = 2; t < NTD; ++t)
; #pragma unroll
;                     for (int j = 0; j < 4; ++j) { vlo[(t - 2) * 4 + j] = vtr(Vb + trb + (16 * j) * VP + t * 64); vhi[(t - 2) * 4 + j] = vtr(Vb + trb + (16 * j + 8) * VP + t * 64); }
;                 __builtin_amdgcn_sched_barrier(0);
; #pragma unroll
;                 for (int t = 2; t < NTD; ++t)
; #pragma unroll
;                     for (int j = 0; j < 4; ++j) {
;                         const int i = (t - 2) * 4 + j;
;                         const bf16x8 vf = (bf16x8){vlo[i][0], vlo[i][1], vlo[i][2], vlo[i][3], vhi[i][0], vhi[i][1], vhi[i][2], vhi[i][3]};
;                         o[t] = __builtin_amdgcn_mfma_f32_32x32x16_bf16(vf, pw[j], o[t], 0, 0, 0);
;                     }
;             }
.Ldb_last:
	s_waitcnt lgkmcnt(14)
	v_mfma_f32_32x32x16_bf16 v[34:49], v[90:93], v[98:101], v[34:49]
	ds_read_b64_tr_b16 v[160:161], v236 offset:17536
	ds_read_b64_tr_b16 v[162:163], v236 offset:20096
	s_waitcnt lgkmcnt(14)
	v_mfma_f32_32x32x16_bf16 v[50:65], v[94:97], v[98:101], v[50:65]
	ds_read_b64_tr_b16 v[164:165], v236 offset:17600
	ds_read_b64_tr_b16 v[166:167], v236 offset:20160
	s_waitcnt lgkmcnt(14)
	v_mfma_f32_32x32x16_bf16 v[34:49], v[106:109], v[102:105], v[34:49]
	ds_read_b64_tr_b16 v[168:169], v236 offset:22656
	ds_read_b64_tr_b16 v[170:171], v236 offset:25216
	s_waitcnt lgkmcnt(14)
	v_mfma_f32_32x32x16_bf16 v[50:65], v[110:113], v[102:105], v[50:65]
	ds_read_b64_tr_b16 v[172:173], v236 offset:22720
	ds_read_b64_tr_b16 v[174:175], v236 offset:25280
	s_waitcnt lgkmcnt(14)
	v_mfma_f32_32x32x16_bf16 v[34:49], v[240:243], v[82:85], v[34:49]
	ds_read_b64_tr_b16 v[176:177], v236 offset:27776
	ds_read_b64_tr_b16 v[178:179], v236 offset:30336
	s_waitcnt lgkmcnt(14)
	v_mfma_f32_32x32x16_bf16 v[50:65], v[148:151], v[82:85], v[50:65]
	ds_read_b64_tr_b16 v[90:91], v236 offset:27840
	ds_read_b64_tr_b16 v[92:93], v236 offset:30400
	s_waitcnt lgkmcnt(14)
	v_mfma_f32_32x32x16_bf16 v[50:65], v[152:155], v[86:89], v[50:65]
	ds_read_b64_tr_b16 v[94:95], v236 offset:32896
	ds_read_b64_tr_b16 v[96:97], v236 offset:35456
	s_waitcnt lgkmcnt(14)
	v_mfma_f32_32x32x16_bf16 v[34:49], v[156:159], v[86:89], v[34:49]
	ds_read_b64_tr_b16 v[106:107], v236 offset:32960
	ds_read_b64_tr_b16 v[108:109], v236 offset:35520
	s_waitcnt lgkmcnt(14)
	v_mfma_f32_32x32x16_bf16 v[18:33], v[160:163], v[98:101], v[18:33]
	s_waitcnt lgkmcnt(12)
	v_mfma_f32_32x32x16_bf16 v[2:17], v[164:167], v[98:101], v[2:17]
	s_waitcnt lgkmcnt(10)
	v_mfma_f32_32x32x16_bf16 v[18:33], v[168:171], v[102:105], v[18:33]
	s_waitcnt lgkmcnt(8)
	v_mfma_f32_32x32x16_bf16 v[2:17], v[172:175], v[102:105], v[2:17]
	s_waitcnt lgkmcnt(6)
	v_mfma_f32_32x32x16_bf16 v[18:33], v[176:179], v[82:85], v[18:33]
	s_waitcnt lgkmcnt(4)
	v_mfma_f32_32x32x16_bf16 v[2:17], v[90:93], v[82:85], v[2:17]
	s_waitcnt lgkmcnt(2)
	v_mfma_f32_32x32x16_bf16 v[18:33], v[94:97], v[86:89], v[18:33]
	s_waitcnt lgkmcnt(0)
	v_mfma_f32_32x32x16_bf16 v[2:17], v[106:109], v[86:89], v[2:17]
	s_branch .Ldb_stores
.Ldb_first:
	v_add_u32_e32 v239, s45, v234
	ds_read_b128 v[148:151], v239
	ds_read_b128 v[152:155], v239 offset:8704
	ds_read_b128 v[156:159], v239 offset:32
	ds_read_b128 v[160:163], v239 offset:8736
	ds_read_b128 v[164:167], v239 offset:64
	ds_read_b128 v[168:171], v239 offset:8768
	ds_read_b128 v[172:175], v239 offset:96
	ds_read_b128 v[176:179], v239 offset:8800
	s_waitcnt lgkmcnt(7)
	v_mfma_f32_32x32x16_bf16 v[98:113], v[148:151], v[116:119], v[66:81]
	s_waitcnt lgkmcnt(6)
	v_mfma_f32_32x32x16_bf16 v[82:97], v[152:155], v[116:119], v[66:81]
	s_waitcnt lgkmcnt(5)
	v_mfma_f32_32x32x16_bf16 v[98:113], v[156:159], v[120:123], v[98:113]
	s_waitcnt lgkmcnt(4)
	v_mfma_f32_32x32x16_bf16 v[82:97], v[160:163], v[120:123], v[82:97]
	s_waitcnt lgkmcnt(3)
	v_mfma_f32_32x32x16_bf16 v[98:113], v[164:167], v[124:127], v[98:113]
	s_waitcnt lgkmcnt(2)
	v_mfma_f32_32x32x16_bf16 v[82:97], v[168:171], v[124:127], v[82:97]
	s_waitcnt lgkmcnt(1)
	v_mfma_f32_32x32x16_bf16 v[98:113], v[172:175], v[128:131], v[98:113]
	s_waitcnt lgkmcnt(0)
	v_mfma_f32_32x32x16_bf16 v[82:97], v[176:179], v[128:131], v[82:97]

; template <bool DIFF>
; __device__ __forceinline__ void attn_unit(const AttnP& A, int b, int h, int qi, ldsp lds) {
;     ...
;         if (kt + 1 < nt) STORE_TILE((kt + 1) & 1);
;         __syncthreads();
;     }
.Lda15_snov:
	s_waitcnt lgkmcnt(0)
	s_barrier
	s_add_i32 s75, s75, 1
	s_add_i32 s74, s74, 64
	s_cmp_le_i32 s75, s31
	s_cbranch_scc1 .Ldb_top
	s_branch .LBB0_515
